# retention: K-tile LDS-DMA issued one phase earlier (after the P-exchange barrier of the previous tile, in the partner-P wait window) instead of inside the S-phase MFMA chain; tile-end wait vmcnt(4); p
# speedup vs baseline: 1.0066x; 1.0066x over previous
; __device__ __forceinline__ void p2_ret(const Frame& F, ArgsP a, int layer) {
;     ...
;         const int bh = it >> 3, p = it & 7, b = bh >> 3, h = bh & 7;
;         const float e = __builtin_amdgcn_exp2f((float)(-5 - h));
;         const float lg2 = -(e * (1.f + e * (0.5f + e * (0.33333334f + e * (0.25f + e * (0.2f + e * 0.16666667f)))))) * 1.4426950408889634f;
;     ...
;         bf16x8 qf[16];
;         RT_PREFETCH(15 - p);
.LBB0_353:
	s_and_b32 s50, s95, 7
	s_ashr_i32 s2, s95, 6
	s_ashr_i32 s3, s2, 31
	s_xor_b32 s89, s50, 15
	s_lshl_b64 s[66:67], s[2:3], 11
	v_lshl_or_b32 v0, s89, 7, v226
	v_or_b32_e32 v34, s66, v0
	v_mov_b32_e32 v35, s67
	v_readlane_b32 s6, v255, 30
	s_bfe_u32 s4, s95, 0x30003
	v_lshlrev_b64 v[36:37], 12, v[34:35]
	v_readlane_b32 s7, v255, 31
	s_lshl_b32 s20, s4, 9
	v_mov_b32_e32 v221, v1
	v_lshl_add_u64 v[36:37], s[6:7], 0, v[36:37]
	v_lshl_add_u64 v[36:37], v[36:37], 0, s[20:21]
	v_lshl_add_u64 v[36:37], v[36:37], 0, v[220:221]
	global_load_dwordx4 v[118:121], v[36:37], off
	global_load_dwordx4 v[122:125], v[36:37], off offset:32
	global_load_dwordx4 v[126:129], v[36:37], off offset:64
	global_load_dwordx4 v[130:133], v[36:37], off offset:96
	global_load_dwordx4 v[134:137], v[36:37], off offset:128
	global_load_dwordx4 v[138:141], v[36:37], off offset:160
	global_load_dwordx4 v[142:145], v[36:37], off offset:192
	global_load_dwordx4 v[146:149], v[36:37], off offset:224
	global_load_dwordx4 v[150:153], v[36:37], off offset:256
	global_load_dwordx4 v[154:157], v[36:37], off offset:288
	global_load_dwordx4 v[158:161], v[36:37], off offset:320
	global_load_dwordx4 v[162:165], v[36:37], off offset:352
	global_load_dwordx4 v[166:169], v[36:37], off offset:384
	global_load_dwordx4 v[170:173], v[36:37], off offset:416
	global_load_dwordx4 v[174:177], v[36:37], off offset:448
	global_load_dwordx4 v[178:181], v[36:37], off offset:480
	s_lshl_b32 s5, s2, 23
	s_mov_b32 m0, s22
	s_or_b32 s17, s20, s5
	v_readlane_b32 s5, v254, 8
	buffer_load_dwordx4 v224, s[40:43], s17 offen lds
	s_or_b32 s56, s17, 0x10000
	s_mov_b32 m0, s5
	v_readlane_b32 s5, v254, 9
	buffer_load_dwordx4 v224, s[40:43], s56 offen lds
	s_or_b32 s57, s17, 0x20000
	s_mov_b32 m0, s5
	v_readlane_b32 s5, v254, 10
	s_lshl_b32 s3, s2, 11
	buffer_load_dwordx4 v224, s[40:43], s57 offen lds
	s_mov_b32 m0, s5
	s_lshl_b32 s5, s4, 21
	s_or_b32 s34, s17, 0x30000
	s_add_i32 s5, s5, s3
	buffer_load_dwordx4 v224, s[40:43], s34 offen lds
	s_lshl_b32 s10, s5, 1
	s_mov_b32 s46, s42
	s_mov_b32 s47, s43
	s_mov_b32 m0, s33
	v_readlane_b32 s3, v254, 12
	buffer_load_dwordx4 v225, s[44:47], s10 offen lds
	s_add_i32 s52, s10, 0x100000
	s_mov_b32 m0, s3
	v_readlane_b32 s3, v254, 13
	buffer_load_dwordx4 v225, s[44:47], s52 offen lds
	s_add_i32 s65, s10, 0x200000
	s_mov_b32 m0, s3
	v_readlane_b32 s3, v254, 14
	buffer_load_dwordx4 v225, s[44:47], s65 offen lds
	s_add_i32 s16, s10, 0x300000
	s_mov_b32 m0, s3
	s_sub_i32 s3, -5, s4
	buffer_load_dwordx4 v225, s[44:47], s16 offen lds
	s_add_i32 m0, s22, 0x8000
	s_add_i32 s12, s17, 0x40000
	buffer_load_dwordx4 v224, s[40:43], s12 offen lds
	s_add_i32 m0, s22, 0xa000
	s_add_i32 s12, s17, 0x50000
	buffer_load_dwordx4 v224, s[40:43], s12 offen lds
	s_add_i32 m0, s22, 0xc000
	s_add_i32 s12, s17, 0x60000
	buffer_load_dwordx4 v224, s[40:43], s12 offen lds
	s_add_i32 m0, s22, 0xe000
	s_add_i32 s12, s17, 0x70000
	buffer_load_dwordx4 v224, s[40:43], s12 offen lds
	v_cvt_f32_i32_e32 v0, s3
	s_lshl_b32 s25, s4, 22
	s_lshl_b32 s3, s4, 8
	v_readlane_b32 s4, v255, 32
	v_exp_f32_e32 v0, v0
	s_add_u32 s68, s4, s20
	v_readlane_b32 s4, v255, 34
	v_lshl_add_u64 v[36:37], v[210:211], 0, s[20:21]
	v_fmamk_f32 v34, v0, 0x3e2aaaab, v233
	v_fmaak_f32 v34, v0, v34, 0x3e800000
	v_fmaak_f32 v34, v0, v34, 0x3eaaaaab
	v_fma_f32 v34, v0, v34, 0.5
	v_fma_f32 v34, v0, v34, 1.0
	v_mul_f32_e32 v0, v0, v34
	v_mul_f32_e32 v221, 0xbfb8aa3b, v0
	v_lshl_or_b32 v0, s50, 7, v226
	v_or_b32_e32 v34, s66, v0
	v_lshlrev_b64 v[34:35], 12, v[34:35]
	s_addc_u32 s69, s4, 0
	s_lshl_b32 s2, s2, 12
	v_lshl_add_u64 v[222:223], v[36:37], 0, v[34:35]
	s_add_i32 s25, s25, s2
	s_or_b32 s88, s17, 0x70000
	s_mov_b64 s[74:75], -1
	s_lshl_b32 s20, s3, 1
	s_branch .LBB0_355

; #define LAS __attribute__((address_space(3)))
; #define RT_DMA_K(kt_, bf_, i_) __builtin_amdgcn_raw_ptr_buffer_load_lds(RK, (LAS void*)(lds + RT_K0 + (bf_) * 32768 + (w + 8 * (i_)) * 1024), 16, (int)RT_KOFF, (int)((unsigned)((b * SEQ + (kt_) * 64) * DR + h * 256) * 2u + (i_) * 65536u), 0, 0)
; #define RT_DMA_V(kt_, bf_, i_) __builtin_amdgcn_raw_ptr_buffer_load_lds(RV, (LAS void*)(lds + RT_V0 + (bf_) * 32768 + (w + 8 * (i_)) * 1024), 16, (int)RT_VOFF, (int)((unsigned)((h * 256) * MTOK + b * SEQ + (kt_) * 64) * 2u + (i_) * 1048576u), 0, 0)
; #define RT_KRD(dst, s0) do { _Pragma("unroll") for (int j_ = 0; j_ < 2; ++j_) dst[j_] = *(const LAS bf16x8*)(kb + ((((2 * ((s0) + j_)) | hh) ^ x15) << 4)); } while (0)
; #define RT_KMM(src, s0) do { _Pragma("unroll") for (int j_ = 0; j_ < 2; ++j_) st = __builtin_amdgcn_mfma_f32_32x32x16_bf16(src[j_], qf[(s0) + j_], st, 0, 0, 0); } while (0)
; __device__ __forceinline__ void p2_ret(const Frame& F, ArgsP a, int layer) {
;     ...
;                 { const LAS unsigned char* kb = lds + RT_K0 + bf * 32768 + (32 * wc + kap) * 512;
;     ...
;                   bf16x8 ka[2], kd[2], kc[2];
;                   RT_KRD(ka, 0); RT_KRD(kd, 2); __builtin_amdgcn_sched_barrier(0);
;                   RT_KRD(kc, 4); RT_KMM(ka, 0); if (pre) { RT_DMA_K(kt + 1, bf ^ 1, 0); RT_DMA_V(kt + 1, bf ^ 1, 0); } __builtin_amdgcn_sched_barrier(0);
;                   RT_KRD(ka, 6); RT_KMM(kd, 2); __builtin_amdgcn_sched_barrier(0);
;                   RT_KRD(kd, 8); RT_KMM(kc, 4); if (pre) { RT_DMA_K(kt + 1, bf ^ 1, 1); RT_DMA_V(kt + 1, bf ^ 1, 1); } __builtin_amdgcn_sched_barrier(0);
;                   RT_KRD(kc, 10); RT_KMM(ka, 6); __builtin_amdgcn_sched_barrier(0);
;                   RT_KRD(ka, 12); RT_KMM(kd, 8); if (pre) { RT_DMA_K(kt + 1, bf ^ 1, 2); RT_DMA_V(kt + 1, bf ^ 1, 2); } __builtin_amdgcn_sched_barrier(0);
;                   RT_KRD(kd, 14); RT_KMM(kc, 10); __builtin_amdgcn_sched_barrier(0);
;                   RT_KMM(ka, 12); if (pre) { RT_DMA_K(kt + 1, bf ^ 1, 3); RT_DMA_V(kt + 1, bf ^ 1, 3); } __builtin_amdgcn_sched_barrier(0);
;                   RT_KMM(kd, 14); __builtin_amdgcn_sched_barrier(0);
.LBB0_383:
	v_mov_b32_e32 v0, v207
	s_and_b32 s6, s31, 0x8000
	v_lshlrev_b32_e32 v99, 1, v0
	v_lshrrev_b32_e32 v100, 1, v0
	v_and_b32_e32 v98, 19, v0
	v_and_b32_e32 v99, 8, v99
	v_and_b32_e32 v100, 4, v100
	v_or3_b32 v115, v99, v98, v100
	v_ashrrev_i32_e32 v116, 5, v0
	s_add_i32 s4, s6, 0
	v_or_b32_e32 v98, s80, v115
	v_or_b32_e32 v99, 2, v116
	v_lshl_add_u32 v227, v98, 9, s4
	v_bitop3_b32 v98, v115, v116, 15 bitop3:0x6c
	v_bitop3_b32 v99, v115, v99, 15 bitop3:0x6c
	v_lshl_add_u32 v98, v98, 4, v227
	v_lshl_add_u32 v102, v99, 4, v227
	ds_read_b128 v[98:101], v98
	ds_read_b128 v[190:193], v102
	v_or_b32_e32 v102, 4, v116
	v_bitop3_b32 v102, v115, v102, 15 bitop3:0x6c
	v_or_b32_e32 v103, 6, v116
	v_lshl_add_u32 v102, v102, 4, v227
	v_bitop3_b32 v103, v115, v103, 15 bitop3:0x6c
	v_lshl_add_u32 v103, v103, 4, v227
	ds_read_b128 v[194:197], v102
	ds_read_b128 v[198:201], v103
	v_and_b32_e32 v117, 31, v0
	v_add_u32_e32 v216, s23, v116
	v_lshlrev_b32_e32 v217, 12, v216
	v_bitop3_b32 v216, v216, v117, 15 bitop3:0x6c
	v_or_b32_e32 v102, 8, v116
	s_xor_b32 s4, s6, 0x8000
	v_lshl_or_b32 v228, v216, 4, v217
	v_lshrrev_b32_e32 v217, 4, v0
	v_bitop3_b32 v102, v115, v102, 15 bitop3:0x6c
	v_or_b32_e32 v103, 10, v116
	s_add_i32 s5, s22, s4
	v_add_u32_e32 v217, s90, v217
	v_lshl_add_u32 v102, v102, 4, v227
	v_bitop3_b32 v103, v115, v103, 15 bitop3:0x6c
	s_add_i32 s7, s27, 0xfffd0000
	v_lshrrev_b32_e32 v216, 3, v0
	v_xor_b32_e32 v217, v217, v0
	v_lshl_add_u32 v103, v103, 4, v227
	ds_read_b128 v[202:205], v102
	ds_read_b128 v[212:215], v103
	v_add_lshl_u32 v216, v216, s35, 14
	v_lshlrev_b32_e32 v217, 4, v217
	s_movk_i32 s7, 0x70
	v_and_or_b32 v229, v217, s7, v216
	s_add_i32 s7, s25, s30
	s_add_i32 m0, s33, s4
	s_add_i32 s12, s7, 0x80
	s_mov_b32 s46, s42
	s_mov_b32 s47, s43
	buffer_load_dwordx4 v229, s[44:47], s12 offen lds
	s_waitcnt lgkmcnt(5)
	v_mfma_f32_32x32x16_bf16 v[98:113], v[98:101], v[118:121], 0
	s_waitcnt lgkmcnt(4)
	v_mfma_f32_32x32x16_bf16 v[98:113], v[190:193], v[122:125], v[98:113]
	v_or_b32_e32 v190, 12, v116
	v_or_b32_e32 v191, 14, v116
	v_bitop3_b32 v190, v115, v190, 15 bitop3:0x6c
	v_bitop3_b32 v191, v115, v191, 15 bitop3:0x6c
	v_lshl_add_u32 v190, v190, 4, v227
	v_lshl_add_u32 v216, v191, 4, v227
	ds_read_b128 v[190:193], v190
	ds_read_b128 v[216:219], v216
	s_waitcnt lgkmcnt(5)
	v_mfma_f32_32x32x16_bf16 v[98:113], v[194:197], v[126:129], v[98:113]
	v_or_b32_e32 v194, 16, v116
	v_or_b32_e32 v195, 18, v116
	v_bitop3_b32 v194, v115, v194, 15 bitop3:0x6c
	v_bitop3_b32 v195, v115, v195, 15 bitop3:0x6c
	s_add_i32 s4, s4, 0
	v_lshl_add_u32 v194, v194, 4, v227
	s_waitcnt lgkmcnt(4)
	v_mfma_f32_32x32x16_bf16 v[98:113], v[198:201], v[130:133], v[98:113]
	v_lshl_add_u32 v198, v195, 4, v227
	s_add_i32 s12, s27, 0xfffe0000
	s_add_i32 s4, s4, 0x10000
	ds_read_b128 v[194:197], v194
	ds_read_b128 v[198:201], v198
	s_add_i32 m0, s4, s24
	s_add_i32 s12, s7, 0x100080
	buffer_load_dwordx4 v229, s[44:47], s12 offen lds
	s_waitcnt lgkmcnt(5)
	v_mfma_f32_32x32x16_bf16 v[98:113], v[202:205], v[134:137], v[98:113]
	s_waitcnt lgkmcnt(4)
	v_mfma_f32_32x32x16_bf16 v[98:113], v[212:215], v[138:141], v[98:113]
	v_or_b32_e32 v202, 20, v116
	v_or_b32_e32 v203, 22, v116
	v_bitop3_b32 v202, v115, v202, 15 bitop3:0x6c
	v_bitop3_b32 v203, v115, v203, 15 bitop3:0x6c
	v_lshl_add_u32 v202, v202, 4, v227
	v_lshl_add_u32 v212, v203, 4, v227
	ds_read_b128 v[202:205], v202
	ds_read_b128 v[212:215], v212
	s_waitcnt lgkmcnt(5)
	v_mfma_f32_32x32x16_bf16 v[98:113], v[190:193], v[142:145], v[98:113]
	v_or_b32_e32 v190, 24, v116
	v_or_b32_e32 v191, 26, v116
	v_bitop3_b32 v190, v115, v190, 15 bitop3:0x6c
	v_bitop3_b32 v191, v115, v191, 15 bitop3:0x6c
	v_lshl_add_u32 v190, v190, 4, v227
	s_add_i32 s12, s27, 0xffff0000
	s_waitcnt lgkmcnt(4)
	v_mfma_f32_32x32x16_bf16 v[98:113], v[216:219], v[146:149], v[98:113]
	v_lshl_add_u32 v216, v191, 4, v227
	ds_read_b128 v[190:193], v190
	ds_read_b128 v[216:219], v216
	s_add_i32 m0, s4, s26
	s_add_i32 s12, s7, 0x200080
	buffer_load_dwordx4 v229, s[44:47], s12 offen lds
	s_waitcnt lgkmcnt(5)
	v_mfma_f32_32x32x16_bf16 v[98:113], v[194:197], v[150:153], v[98:113]
	s_waitcnt lgkmcnt(4)
	v_mfma_f32_32x32x16_bf16 v[98:113], v[198:201], v[154:157], v[98:113]
	s_waitcnt lgkmcnt(3)
	v_mfma_f32_32x32x16_bf16 v[98:113], v[202:205], v[158:161], v[98:113]
	v_or_b32_e32 v194, 28, v116
	v_or_b32_e32 v195, 30, v116
	v_bitop3_b32 v194, v115, v194, 15 bitop3:0x6c
	v_bitop3_b32 v195, v115, v195, 15 bitop3:0x6c
	v_lshl_add_u32 v194, v194, 4, v227
	v_lshl_add_u32 v198, v195, 4, v227
	ds_read_b128 v[194:197], v194
	ds_read_b128 v[198:201], v198
	s_waitcnt lgkmcnt(4)
	v_mfma_f32_32x32x16_bf16 v[98:113], v[212:215], v[162:165], v[98:113]
	s_add_i32 s7, s7, 0x300080
	s_add_i32 m0, s4, s28
	s_waitcnt lgkmcnt(3)
	v_mfma_f32_32x32x16_bf16 v[98:113], v[190:193], v[166:169], v[98:113]
	buffer_load_dwordx4 v229, s[44:47], s7 offen lds
	s_waitcnt lgkmcnt(2)
	v_mfma_f32_32x32x16_bf16 v[98:113], v[216:219], v[170:173], v[98:113]
	s_waitcnt lgkmcnt(1)
	v_mfma_f32_32x32x16_bf16 v[98:113], v[194:197], v[174:177], v[98:113]
	s_waitcnt lgkmcnt(0)
	v_mfma_f32_32x32x16_bf16 v[98:113], v[198:201], v[178:181], v[98:113]
	v_lshlrev_b32_e32 v250, 3, v115
	v_and_b32_e32 v250, 0x70, v250
	s_add_i32 s13, s64, s6
	v_lshl_add_u32 v251, v115, 7, s13
	v_lshlrev_b32_e32 v252, 4, v116
	s_lshl_b32 s14, s80, 1
	v_xad_u32 v246, v250, v252, v251
	v_add_u32_e32 v253, 32, v252
	v_xad_u32 v247, v250, v253, v251
	v_xor_b32_e32 v246, s14, v246
	v_xor_b32_e32 v247, s14, v247
	v_xor_b32_e32 v248, 64, v246
	v_xor_b32_e32 v249, 64, v247
	ds_read_b128 v[234:237], v246
	ds_read_b128 v[238:241], v247
	s_cmp_ge_u32 s91, s29
	s_mov_b64 s[4:5], -1
	s_cbranch_scc0 .LBB0_385
; __device__ __forceinline__ unsigned cvt_pk_bf16(float lo, float hi) { unsigned r; asm volatile("v_cvt_pk_bf16_f32 %0, %1, %2" : "=v"(r) : "v"(lo), "v"(hi)); return r; }
; __device__ __forceinline__ void p2_ret(const Frame& F, ArgsP a, int layer) {
;     ...
;                   } else { const int lim = wr * 32 + l31 + (2 * qi - kt) * 64 - 32 * wc - 8 * hh;
; #pragma unroll
;                       for (int i = 0; i < 8; ++i) { const int r0 = 2 * i, r1 = 2 * i + 1, o0 = 16 * (r0 >> 3) + (r0 & 7), o1 = 16 * (r1 >> 3) + (r1 & 7);
;                           pk[i] = cvt_pk_bf16((o0 <= lim) ? st[r0] : 0.f, (o1 <= lim) ? st[r1] : 0.f); } }
	v_lshlrev_b32_e32 v190, 3, v116
	v_sub_u32_e32 v117, v117, v190
	v_add_u32_e32 v117, s97, v117
	v_cmp_lt_i32_e32 vcc, -1, v117
	s_mov_b64 s[4:5], 0
	s_nop 3
	v_cndmask_b32_e32 v190, 0, v98, vcc
	v_cmp_lt_i32_e32 vcc, 0, v117
	s_nop 1
	v_cndmask_b32_e32 v191, 0, v99, vcc
	v_cmp_lt_i32_e32 vcc, 1, v117
	v_cvt_pk_bf16_f32 v190, v190, v191
	s_nop 1
	v_cndmask_b32_e32 v191, 0, v100, vcc
	v_cmp_lt_i32_e32 vcc, 2, v117
	s_nop 1
	v_cndmask_b32_e32 v192, 0, v101, vcc
	v_cmp_lt_i32_e32 vcc, 3, v117
	v_cvt_pk_bf16_f32 v191, v191, v192
	s_nop 1
	v_cndmask_b32_e32 v192, 0, v102, vcc
	v_cmp_lt_i32_e32 vcc, 4, v117
	s_nop 1
	v_cndmask_b32_e32 v193, 0, v103, vcc
	v_cmp_lt_i32_e32 vcc, 5, v117
	v_cvt_pk_bf16_f32 v192, v192, v193
	s_nop 1
	v_cndmask_b32_e32 v193, 0, v104, vcc
	v_cmp_lt_i32_e32 vcc, 6, v117
	s_nop 1
	v_cndmask_b32_e32 v194, 0, v105, vcc
	v_cmp_lt_i32_e32 vcc, 15, v117
	v_cvt_pk_bf16_f32 v193, v193, v194
	s_nop 1
	v_cndmask_b32_e32 v194, 0, v106, vcc
	v_cmp_lt_i32_e32 vcc, 16, v117
	s_nop 1
	v_cndmask_b32_e32 v195, 0, v107, vcc
	v_cmp_lt_i32_e32 vcc, 17, v117
	v_cvt_pk_bf16_f32 v194, v194, v195
	s_nop 1
	v_cndmask_b32_e32 v195, 0, v108, vcc
	v_cmp_lt_i32_e32 vcc, 18, v117
	s_nop 1
	v_cndmask_b32_e32 v196, 0, v109, vcc
	v_cmp_lt_i32_e32 vcc, 19, v117
	v_cvt_pk_bf16_f32 v195, v195, v196
	s_nop 1
	v_cndmask_b32_e32 v196, 0, v110, vcc
	v_cmp_lt_i32_e32 vcc, 20, v117
	s_nop 1
	v_cndmask_b32_e32 v197, 0, v111, vcc
	v_cmp_lt_i32_e32 vcc, 21, v117
	v_cvt_pk_bf16_f32 v196, v196, v197
	s_nop 1
	v_cndmask_b32_e32 v197, 0, v112, vcc
	v_cmp_lt_i32_e32 vcc, 22, v117
	s_nop 1
	v_cndmask_b32_e32 v117, 0, v113, vcc
	v_cvt_pk_bf16_f32 v197, v197, v117

; #define LAS __attribute__((address_space(3)))
; #define RT_BAR() do { asm volatile("s_waitcnt lgkmcnt(0)" ::: "memory"); __builtin_amdgcn_s_barrier(); asm volatile("" ::: "memory"); } while (0)
; #define RT_VRD(dst, g) do { _Pragma("unroll") for (int j_ = 0; j_ < 2; ++j_) { const int jj_ = 2 * ((g) & 1) + j_; dst[j_] = *(const LAS bf16x8*)(vb + ((g) >> 1) * 4096 + (((4 * (jj_ >> 1) + 2 * (jj_ & 1) + hh) << 4) ^ m4)); } } while (0)
; __device__ __forceinline__ void p2_ret(const Frame& F, ArgsP a, int layer) {
;     ...
;                   LAS unsigned char* pw = lds + RT_P + ((wr * 2 + wc) * 2) * 1024 + lane * 16;
;                   *(LAS u32x4*)pw = (u32x4){pk[0], pk[1], pk[2], pk[3]}; *(LAS u32x4*)(pw + 1024) = (u32x4){pk[4], pk[5], pk[6], pk[7]}; }
;                 RT_BAR();
;                 { bf16x8 pf[2][2];
; #pragma unroll
;                   for (int kb2 = 0; kb2 < 2; ++kb2)
; #pragma unroll
;                       for (int s = 0; s < 2; ++s) pf[kb2][s] = *(const LAS bf16x8*)(lds + RT_P + ((wr * 2 + kb2) * 2 + s) * 1024 + lane * 16);
;                   const LAS unsigned char* vb = lds + RT_V0 + bf * 32768 + (128 * wc + kap) * 128;
;     ...
;                   bf16x8 va[2], vc[2];
;                   RT_VRD(va, 0); __builtin_amdgcn_sched_barrier(0);
;                   RT_VRD(vc, 1); RT_VMM(va, 0); __builtin_amdgcn_sched_barrier(0);
;                   RT_VRD(va, 2); RT_VMM(vc, 1); __builtin_amdgcn_sched_barrier(0);
;                   RT_VRD(vc, 3); RT_VMM(va, 2); __builtin_amdgcn_sched_barrier(0);
;                   RT_VRD(va, 4); RT_VMM(vc, 3); __builtin_amdgcn_sched_barrier(0);
;                   RT_VRD(vc, 5); RT_VMM(va, 4); __builtin_amdgcn_sched_barrier(0);
;                   RT_VRD(va, 6); RT_VMM(vc, 5); __builtin_amdgcn_sched_barrier(0);
;                   RT_VRD(vc, 7); RT_VMM(va, 6); __builtin_amdgcn_sched_barrier(0);
;                   RT_VMM(vc, 7); __builtin_amdgcn_sched_barrier(0);
;     ...
;                 }
;                 asm volatile("s_waitcnt vmcnt(0)" ::: "memory");
;                 if (cv) { const CvU cu = cv_decode(a, F.ws, cvhi, layer); cv_store(cu, lane, cvv, cvsc); cvhi += cvs; }
;                 RT_BAR();
.LBB0_387:
	s_nop 6
	v_lshlrev_b32_e32 v98, 4, v0
	v_add_u32_e32 v99, s83, v98
	ds_write_b128 v99, v[190:193]
	ds_write_b128 v99, v[194:197] offset:1024
	s_lshl_b32 s12, s80, 6
	s_sub_i32 s12, 0x800, s12
	s_add_i32 s12, s12, s82
	v_add_u32_e32 v250, s12, v98
	ds_read_b128 v[242:245], v246 offset:4096
	ds_read_b128 v[106:109], v247 offset:4096
	s_waitcnt lgkmcnt(5)
	v_mfma_f32_32x32x16_bf16 v[82:97], v[234:237], v[190:193], v[82:97]
	s_waitcnt lgkmcnt(4)
	v_mfma_f32_32x32x16_bf16 v[82:97], v[238:241], v[194:197], v[82:97]
	ds_read_b128 v[234:237], v246 offset:8192
	ds_read_b128 v[238:241], v247 offset:8192
	s_waitcnt lgkmcnt(3)
	v_mfma_f32_32x32x16_bf16 v[66:81], v[242:245], v[190:193], v[66:81]
	s_waitcnt lgkmcnt(2)
	v_mfma_f32_32x32x16_bf16 v[66:81], v[106:109], v[194:197], v[66:81]
	ds_read_b128 v[242:245], v246 offset:12288
	ds_read_b128 v[106:109], v247 offset:12288
	s_waitcnt lgkmcnt(3)
	v_mfma_f32_32x32x16_bf16 v[50:65], v[234:237], v[190:193], v[50:65]
	s_waitcnt lgkmcnt(2)
	v_mfma_f32_32x32x16_bf16 v[50:65], v[238:241], v[194:197], v[50:65]
	ds_read_b128 v[234:237], v248
	ds_read_b128 v[238:241], v249
	s_barrier
	ds_read_b128 v[98:101], v250
	ds_read_b128 v[102:105], v250 offset:1024
	s_add_i32 s12, s30, 0x80
	s_cmp_eq_u32 s12, s11
	s_cbranch_scc1 .Lrk_skip
	s_add_i32 s13, s22, s6
	s_mov_b32 m0, s13
	s_add_i32 s12, s27, 0x10000
	buffer_load_dwordx4 v224, s[40:43], s12 offen lds
	s_add_i32 m0, s13, 0x2000
	s_add_i32 s12, s27, 0x20000
	buffer_load_dwordx4 v224, s[40:43], s12 offen lds
	s_add_i32 m0, s13, 0x4000
	s_add_i32 s12, s27, 0x30000
	buffer_load_dwordx4 v224, s[40:43], s12 offen lds
	s_add_i32 m0, s13, 0x6000
	s_add_i32 s12, s27, 0x40000
	buffer_load_dwordx4 v224, s[40:43], s12 offen lds
.Lrk_skip:
	s_waitcnt lgkmcnt(5)
	v_mfma_f32_32x32x16_bf16 v[34:49], v[242:245], v[190:193], v[34:49]
	s_waitcnt lgkmcnt(4)
	v_mfma_f32_32x32x16_bf16 v[34:49], v[106:109], v[194:197], v[34:49]
	ds_read_b128 v[242:245], v248 offset:4096
	ds_read_b128 v[106:109], v249 offset:4096
	s_waitcnt lgkmcnt(2)
	v_mfma_f32_32x32x16_bf16 v[82:97], v[234:237], v[98:101], v[82:97]
	v_mfma_f32_32x32x16_bf16 v[82:97], v[238:241], v[102:105], v[82:97]
	ds_read_b128 v[234:237], v248 offset:8192
	ds_read_b128 v[238:241], v249 offset:8192
	s_waitcnt lgkmcnt(3)
	v_mfma_f32_32x32x16_bf16 v[66:81], v[242:245], v[98:101], v[66:81]
	s_waitcnt lgkmcnt(2)
	v_mfma_f32_32x32x16_bf16 v[66:81], v[106:109], v[102:105], v[66:81]
	ds_read_b128 v[242:245], v248 offset:12288
	ds_read_b128 v[106:109], v249 offset:12288
	s_waitcnt lgkmcnt(3)
	v_mfma_f32_32x32x16_bf16 v[50:65], v[234:237], v[98:101], v[50:65]
	s_waitcnt lgkmcnt(2)
	v_mfma_f32_32x32x16_bf16 v[50:65], v[238:241], v[102:105], v[50:65]
	s_waitcnt lgkmcnt(1)
	v_mfma_f32_32x32x16_bf16 v[34:49], v[242:245], v[98:101], v[34:49]
	s_waitcnt lgkmcnt(0)
	v_mfma_f32_32x32x16_bf16 v[34:49], v[106:109], v[102:105], v[34:49]
	s_add_i32 s12, s30, 0x80
	s_cmp_eq_u32 s12, s11
	s_cbranch_scc1 .Lrk_w0
	s_waitcnt vmcnt(4)
	s_branch .Lrk_wd

; #define RT_BAR() do { asm volatile("s_waitcnt lgkmcnt(0)" ::: "memory"); __builtin_amdgcn_s_barrier(); asm volatile("" ::: "memory"); } while (0)
; __device__ __forceinline__ void p2_ret(const Frame& F, ArgsP a, int layer) {
;     ...
;                 asm volatile("s_waitcnt vmcnt(0)" ::: "memory");
;                 if (cv) { const CvU cu = cv_decode(a, F.ws, cvhi, layer); cv_store(cu, lane, cvv, cvsc); cvhi += cvs; }
;                 RT_BAR();
.Lrk_wd:
	s_and_b64 vcc, exec, s[38:39]
	s_cbranch_vccnz .LBB0_357
	s_ashr_i32 s14, s36, 1
	s_cmpk_lt_i32 s14, 0x400
	s_cselect_b64 s[4:5], -1, 0
	s_mov_b64 s[70:71], 0
	s_and_b64 vcc, exec, s[4:5]
	s_cbranch_vccnz .LBB0_394
	s_mov_b64 s[46:47], -1
	s_cmpk_gt_u32 s14, 0x13ff
	s_mov_b64 s[6:7], -1
	s_cbranch_scc0 .LBB0_391
	s_add_i32 s12, s14, 0xffffec00
	s_mov_b64 s[6:7], 0

; __device__ __forceinline__ void p2_ret(const Frame& F, ArgsP a, int layer) {
;     ...
;             if (uu == 0) RT_PREFETCH(p);
.LBB0_461:
	s_waitcnt lgkmcnt(0)
	s_barrier
	s_andn2_b64 vcc, exec, s[74:75]
	s_cbranch_vccnz .LBB0_463
	global_load_dwordx4 v[118:121], v[222:223], off
	global_load_dwordx4 v[122:125], v[222:223], off offset:32
	global_load_dwordx4 v[126:129], v[222:223], off offset:64
	global_load_dwordx4 v[130:133], v[222:223], off offset:96
	global_load_dwordx4 v[134:137], v[222:223], off offset:128
	global_load_dwordx4 v[138:141], v[222:223], off offset:160
	global_load_dwordx4 v[142:145], v[222:223], off offset:192
	global_load_dwordx4 v[146:149], v[222:223], off offset:224
	global_load_dwordx4 v[150:153], v[222:223], off offset:256
	global_load_dwordx4 v[154:157], v[222:223], off offset:288
	global_load_dwordx4 v[158:161], v[222:223], off offset:320
	global_load_dwordx4 v[162:165], v[222:223], off offset:352
	global_load_dwordx4 v[166:169], v[222:223], off offset:384
	global_load_dwordx4 v[170:173], v[222:223], off offset:416
	global_load_dwordx4 v[174:177], v[222:223], off offset:448
	global_load_dwordx4 v[178:181], v[222:223], off offset:480
	s_mov_b32 m0, s22
	v_readlane_b32 s4, v254, 8
	buffer_load_dwordx4 v224, s[40:43], s17 offen lds
	s_mov_b32 m0, s4
	v_readlane_b32 s4, v254, 9
	buffer_load_dwordx4 v224, s[40:43], s56 offen lds
	s_mov_b32 m0, s4
	v_readlane_b32 s4, v254, 10
	buffer_load_dwordx4 v224, s[40:43], s57 offen lds
	s_mov_b32 m0, s4
	s_mov_b32 s46, s42
	buffer_load_dwordx4 v224, s[40:43], s34 offen lds
	s_mov_b32 s47, s43
	s_mov_b32 m0, s33
	v_readlane_b32 s4, v254, 12
	buffer_load_dwordx4 v225, s[44:47], s10 offen lds
	s_mov_b32 m0, s4
	v_readlane_b32 s4, v254, 13
	buffer_load_dwordx4 v225, s[44:47], s52 offen lds
	s_mov_b32 m0, s4
	v_readlane_b32 s4, v254, 14
	buffer_load_dwordx4 v225, s[44:47], s65 offen lds
	s_mov_b32 m0, s4
	s_nop 0
	buffer_load_dwordx4 v225, s[44:47], s16 offen lds
	s_add_i32 m0, s22, 0x8000
	s_add_i32 s12, s17, 0x40000
	buffer_load_dwordx4 v224, s[40:43], s12 offen lds
	s_add_i32 m0, s22, 0xa000
	s_add_i32 s12, s17, 0x50000
	buffer_load_dwordx4 v224, s[40:43], s12 offen lds
	s_add_i32 m0, s22, 0xc000
	s_add_i32 s12, s17, 0x60000
	buffer_load_dwordx4 v224, s[40:43], s12 offen lds
	s_add_i32 m0, s22, 0xe000
	s_add_i32 s12, s17, 0x70000
	buffer_load_dwordx4 v224, s[40:43], s12 offen lds
